# waves 4-7 delay their first K-fragment LDS reads of each tile by s_sleep 2 so waves 0-3 (prio 1) get the LDS first
# baseline (speedup 1.0000x reference)
; #define LAS __attribute__((address_space(3)))
; #define GAS __attribute__((address_space(1)))
; #define ATT_ISSUE(t) do { const int trow_ = (sample && (t) == 32) ? kvnew : kv0 + 64 * (t); \
;         _Pragma("unroll") for (int i_ = 0; i_ < 3; ++i_) kreg[i_] = *(const GAS u32x4*)(kb[i_] + (size_t)trow_ * ks[i_]); \
;         _Pragma("unroll") for (int i_ = 0; i_ < 2; ++i_) vreg[i_] = *(const GAS u32x4*)(vb[i_] + (size_t)trow_ * 2); } while (0)
; __device__ __forceinline__ void unit(LAS unsigned char* lds, const Tensors& T, int h, int qrow0, int nact, bool sample, int limbase, int kv0, int kvnew, int nt) {
;     int tid_ = threadIdx.x; asm volatile("" : "+v"(tid_));
;     const int tid = tid_, lane = tid & 63, r32 = lane & 31, hi = lane >> 5; const int wid = __builtin_amdgcn_readfirstlane(tid >> 6);
;     const bool active = wid < nact;
;     const int lim = sample ? limbase : limbase + (wid >> 1);
;     const char* kb[3]; int ks[3]; unsigned kd[3];
; #pragma unroll
;     for (int i = 0; i < 3; ++i) { const int c = tid + 512 * i, row = c / 24, cc = c % 24;
;         if (cc < 16) { kb[i] = (const char*)T.KN + ((size_t)row * DM + h * 128 + cc * 8) * 2; ks[i] = DM * 2; }
;         else { kb[i] = (const char*)T.KPE + ((size_t)row * 64 + (cc - 16) * 8) * 2; ks[i] = 64 * 2; }
;         kd[i] = (unsigned)(row * KP + cc * 16); }
;     const char* vb[2]; unsigned vd[2];
; #pragma unroll
;     for (int i = 0; i < 2; ++i) { const int c = tid + 512 * i, drow = c >> 3, cc = c & 7;
;         vb[i] = (const char*)T.VT + ((size_t)(h * 128 + drow) * TA + cc * 8) * 2; vd[i] = (unsigned)(drow * VP + (cc >> 1) * 32 + (cc & 1) * 8); }
;     u32x4 kreg[3], vreg[2];
;     ...
;     ATT_ISSUE(0);
;     bf16x8 qf[12];
;     { const bf16_t* qrow = T.Q + (size_t)(qrow0 + 32 * (active ? wid : 0) + r32) * NQ + h * QKD + hi * 8;
; #pragma unroll
;       for (int d0 = 0; d0 < 12; ++d0) qf[d0] = *(const GAS bf16x8*)(qrow + d0 * 16); }
;     float mrun = -1e30f, lrun = 0.f;
;     f32x16 o[4];
; #pragma unroll
;     for (int d = 0; d < 4; ++d)
; #pragma unroll
;         for (int r = 0; r < 16; ++r) o[d][r] = 0.f;
;     LAS float* scr = (LAS float*)(lds + OFF_SCR + wid * 256);
.LBB0_891:
	v_mov_b32_e32 v214, v206
	s_mov_b32 s0, 0x2aaaaaab
	s_nop 0
	v_mul_hi_i32 v0, v214, s0
	v_lshrrev_b32_e32 v1, 31, v0
	v_ashrrev_i32_e32 v0, 2, v0
	v_add_u32_e32 v6, v0, v1
	v_mul_lo_u32 v0, v6, 24
	v_sub_u32_e32 v18, v214, v0
	v_readfirstlane_b32 s8, v214
	v_cmp_lt_i32_e32 vcc, 15, v18
	v_ashrrev_i32_e32 v7, 31, v6
	s_and_saveexec_b64 s[0:1], vcc
	s_xor_b64 s[0:1], exec, s[0:1]
	v_lshlrev_b64 v[0:1], 7, v[6:7]
	v_lshl_add_u32 v164, v18, 3, v212
	v_lshl_add_u64 v[0:1], s[34:35], 0, v[0:1]
	v_lshl_add_u64 v[0:1], v[164:165], 1, v[0:1]
	s_or_saveexec_b64 s[0:1], s[0:1]
	v_mov_b64_e32 v[2:3], 0x80
	s_xor_b64 exec, exec, s[0:1]
	v_lshlrev_b64 v[0:1], 10, v[6:7]
	v_lshlrev_b32_e32 v2, 3, v18
	v_or_b32_e32 v0, s2, v0
	v_ashrrev_i32_e32 v3, 31, v2
	v_lshl_add_u64 v[0:1], v[0:1], 0, v[2:3]
	v_lshl_add_u64 v[0:1], v[0:1], 1, s[64:65]
	v_mov_b64_e32 v[2:3], 0x800
	s_or_b64 exec, exec, s[0:1]
	v_add_u32_e32 v7, 0x200, v214
	s_mov_b32 s0, 0x2aaaaaab
	v_mul_hi_i32 v3, v7, s0
	v_lshrrev_b32_e32 v4, 31, v3
	v_ashrrev_i32_e32 v3, 2, v3
	v_add_u32_e32 v12, v3, v4
	v_mul_lo_u32 v3, v12, 24
	v_sub_u32_e32 v3, v7, v3
	v_cmp_lt_i32_e32 vcc, 15, v3
	v_ashrrev_i32_e32 v13, 31, v12
	s_and_saveexec_b64 s[0:1], vcc
	s_xor_b64 s[0:1], exec, s[0:1]
	v_lshlrev_b64 v[4:5], 7, v[12:13]
	v_lshl_add_u32 v164, v3, 3, v212
	v_lshl_add_u64 v[4:5], s[34:35], 0, v[4:5]
	v_lshl_add_u64 v[4:5], v[164:165], 1, v[4:5]
	s_or_saveexec_b64 s[0:1], s[0:1]
	v_mov_b64_e32 v[8:9], 0x80
	s_xor_b64 exec, exec, s[0:1]
	v_lshlrev_b64 v[4:5], 10, v[12:13]
	v_lshlrev_b32_e32 v8, 3, v3
	v_or_b32_e32 v4, s2, v4
	v_ashrrev_i32_e32 v9, 31, v8
	v_lshl_add_u64 v[4:5], v[4:5], 0, v[8:9]
	v_lshl_add_u64 v[4:5], v[4:5], 1, s[64:65]
	v_mov_b64_e32 v[8:9], 0x800
	s_or_b64 exec, exec, s[0:1]
	v_add_u32_e32 v9, 0x400, v214
	s_mov_b32 s0, 0x2aaaaaab
	v_mul_hi_i32 v10, v9, s0
	v_lshrrev_b32_e32 v11, 31, v10
	v_ashrrev_i32_e32 v10, 2, v10
	v_add_u32_e32 v16, v10, v11
	v_mul_lo_u32 v10, v16, 24
	v_sub_u32_e32 v9, v9, v10
	v_cmp_lt_i32_e32 vcc, 15, v9
	v_ashrrev_i32_e32 v17, 31, v16
	s_and_saveexec_b64 s[0:1], vcc
	s_xor_b64 s[0:1], exec, s[0:1]
	v_lshlrev_b64 v[10:11], 7, v[16:17]
	v_lshl_add_u32 v164, v9, 3, v212
	v_lshl_add_u64 v[10:11], s[34:35], 0, v[10:11]
	v_lshl_add_u64 v[10:11], v[164:165], 1, v[10:11]
	s_or_saveexec_b64 s[0:1], s[0:1]
	v_mov_b64_e32 v[14:15], 0x80
	s_xor_b64 exec, exec, s[0:1]
	v_lshlrev_b64 v[10:11], 10, v[16:17]
	v_lshlrev_b32_e32 v14, 3, v9
	v_or_b32_e32 v10, s2, v10
	v_ashrrev_i32_e32 v15, 31, v14
	v_lshl_add_u64 v[10:11], v[10:11], 0, v[14:15]
	v_lshl_add_u64 v[10:11], v[10:11], 1, s[64:65]
	v_mov_b64_e32 v[14:15], 0x800
	s_or_b64 exec, exec, s[0:1]
	s_lshr_b32 s0, s47, 4
	s_and_b32 s0, s0, 15
	s_lshl_b32 s29, s27, 8
	s_lshl_b32 s1, s0, 11
	s_add_i32 s4, s29, s3
	s_lshl_b32 s5, s27, 2
	s_ashr_i32 s48, s8, 6
	s_ashr_i32 s8, s8, 7
	s_or_b32 s16, s1, 64
	s_lshl_b32 s94, s0, 12
	v_ashrrev_i32_e32 v17, 3, v214
	v_ashrrev_i32_e32 v40, 3, v7
	s_cmp_lt_i32 s48, 8
	v_and_b32_e32 v13, 7, v214
	v_add_u32_e32 v19, s2, v17
	s_mov_b32 s1, 0x10400
	v_add_u32_e32 v41, s2, v40
	s_cselect_b64 s[40:41], -1, 0
	s_lshl_b32 s0, s28, 12
	v_lshlrev_b32_e32 v15, 3, v13
	v_mad_i64_i32 v[20:21], s[12:13], v19, s1, 0
	v_mad_i64_i32 v[36:37], s[12:13], v41, s1, 0
	s_lshl_b32 s27, s48, 5
	v_or_b32_e32 v20, v20, v15
	v_or_b32_e32 v36, v36, v15
	s_movk_i32 s9, 0x190
	s_cmp_gt_i32 s48, 7
	v_lshl_add_u64 v[32:33], v[20:21], 1, s[66:67]
	s_mov_b32 s1, s95
	v_lshl_add_u64 v[36:37], v[36:37], 1, s[66:67]
	v_mul_lo_u32 v7, v12, s9
	s_cselect_b64 s[22:23], -1, 0
	v_lshl_add_u64 v[32:33], v[32:33], 0, s[0:1]
	v_lshl_add_u64 v[36:37], v[36:37], 0, s[0:1]
	v_lshl_add_u32 v218, v3, 4, v7
	v_mul_lo_u32 v3, v6, s9
	v_and_b32_e32 v216, 31, v214
	s_and_b64 s[0:1], s[22:23], exec
	v_lshl_add_u32 v219, v18, 4, v3
	s_cselect_b32 s0, 0, s27
	v_or_b32_e32 v3, s4, v216
	v_add_u32_e32 v3, s0, v3
	v_mov_b64_e32 v[6:7], s[6:7]
	s_movk_i32 s0, 0xc00
	v_mad_i64_i32 v[6:7], s[0:1], v3, s0, v[6:7]
	v_mad_u64_u32 v[20:21], s[12:13], v2, s3, v[0:1]
	v_bfe_u32 v215, v214, 5, 1
	s_mul_i32 s0, s26, 0x180
	s_mov_b32 s1, s95
	global_load_dwordx4 v[20:23], v[20:21], off
	v_mad_u64_u32 v[24:25], s[12:13], v8, s3, v[4:5]
	v_lshl_add_u64 v[6:7], v[6:7], 0, s[0:1]
	v_lshlrev_b32_e32 v186, 4, v215
	v_mov_b32_e32 v187, v165
	global_load_dwordx4 v[24:27], v[24:25], off
	v_mad_u64_u32 v[28:29], s[12:13], v14, s3, v[10:11]
	v_lshl_add_u64 v[6:7], v[6:7], 0, v[186:187]
	global_load_dwordx4 v[28:31], v[28:29], off
	v_mul_lo_u32 v3, v16, s9
	global_load_dwordx4 v[32:35], v[32:33], off
	v_lshl_add_u32 v220, v9, 4, v3
	global_load_dwordx4 v[36:39], v[36:37], off
	s_nop 0
	global_load_dwordx4 v[140:143], v[6:7], off
	global_load_dwordx4 v[136:139], v[6:7], off offset:32
	global_load_dwordx4 v[132:135], v[6:7], off offset:64
	global_load_dwordx4 v[128:131], v[6:7], off offset:96
	global_load_dwordx4 v[124:127], v[6:7], off offset:128
	global_load_dwordx4 v[120:123], v[6:7], off offset:160
	global_load_dwordx4 v[116:119], v[6:7], off offset:192
	global_load_dwordx4 v[112:115], v[6:7], off offset:224
	global_load_dwordx4 v[108:111], v[6:7], off offset:256
	global_load_dwordx4 v[104:107], v[6:7], off offset:288
	global_load_dwordx4 v[100:103], v[6:7], off offset:320
	global_load_dwordx4 v[96:99], v[6:7], off offset:352
	v_lshlrev_b32_e32 v3, 3, v214
	v_lshlrev_b32_e32 v7, 4, v13
	v_and_b32_e32 v3, 8, v3
	s_movk_i32 s0, 0x60
	v_and_or_b32 v6, v7, s0, v3
	v_add_u32_e32 v3, 0, v219
	s_movk_i32 s4, 0x90
	v_mad_u64_u32 v[188:189], s[0:1], v17, s4, v[6:7]
	v_mad_u64_u32 v[190:191], s[0:1], v40, s4, v[6:7]
	s_lshl_b32 s0, s48, 8
	s_add_i32 s12, s0, 0
	v_mad_u64_u32 v[198:199], s[0:1], v2, s16, v[0:1]
	v_mov_b64_e32 v[0:1], s[94:95]
	s_mov_b32 s4, 0x20800
	v_lshlrev_b32_e32 v200, 6, v2
	v_mad_u64_u32 v[192:193], s[0:1], v14, s16, v[10:11]
	v_lshlrev_b32_e32 v164, 6, v14
	v_mov_b32_e32 v14, v165
	v_mov_b32_e32 v15, v165
	v_and_b32_e32 v187, 63, v214
	s_add_i32 s12, s12, 0x15800
	v_mad_u64_u32 v[194:195], s[0:1], v8, s16, v[4:5]
	v_lshlrev_b32_e32 v196, 6, v8
	v_mov_b32_e32 v4, v165
	v_mov_b32_e32 v5, v165
	v_mov_b32_e32 v6, v165
	v_mov_b32_e32 v8, v165
	v_mov_b32_e32 v9, v165
	v_mov_b32_e32 v10, v165
	v_mov_b32_e32 v11, v165
	v_mov_b32_e32 v12, v165
	v_mov_b32_e32 v13, v165
	s_mov_b32 s9, 0
	s_add_i32 s10, s8, s5
	v_cmp_gt_u32_e64 s[38:39], 32, v187
	v_lshl_add_u32 v189, v216, 2, s12
	s_or_b32 s13, s5, 3
	v_mov_b32_e32 v197, v165
	v_mov_b32_e32 v201, v165
	v_mov_b32_e32 v223, 0xf149f2ca
	v_mov_b32_e32 v191, 0
	s_waitcnt vmcnt(0)
; #define ATT_ISSUE(t) do { const int trow_ = (sample && (t) == 32) ? kvnew : kv0 + 64 * (t); \
;         _Pragma("unroll") for (int i_ = 0; i_ < 3; ++i_) kreg[i_] = *(const GAS u32x4*)(kb[i_] + (size_t)trow_ * ks[i_]); \
;         _Pragma("unroll") for (int i_ = 0; i_ < 2; ++i_) vreg[i_] = *(const GAS u32x4*)(vb[i_] + (size_t)trow_ * 2); } while (0)
; #define ATT_WRITE(buf) do { _Pragma("unroll") for (int i_ = 0; i_ < 3; ++i_) *(LAS u32x4*)(lds + OFF_K + (buf) * KBUF + kd[i_]) = kreg[i_]; \
;         _Pragma("unroll") for (int i_ = 0; i_ < 2; ++i_) { LAS u32x2* d_ = (LAS u32x2*)(lds + OFF_V + (buf) * VBUF + vd[i_]); d_[0] = (u32x2){vreg[i_].x, vreg[i_].y}; d_[2] = (u32x2){vreg[i_].z, vreg[i_].w}; } } while (0)
; __device__ __forceinline__ void unit(LAS unsigned char* lds, const Tensors& T, int h, int qrow0, int nact, bool sample, int limbase, int kv0, int kvnew, int nt) {
;     ...
;     ATT_WRITE(0);
;     __syncthreads();
;     for (int t = 0; t < nt; ++t) {
;         const int buf = t & 1;
;         if (t + 1 < nt) ATT_ISSUE(t + 1);
;         if (active && t <= lim) {
	ds_write_b128 v3, v[20:23]
	v_add_u32_e32 v3, 0, v218
	ds_write_b128 v3, v[24:27]
	v_add_u32_e32 v3, 0, v220
	ds_write_b128 v3, v[28:31]
	v_add_u32_e32 v3, 0, v188
	v_add_u32_e32 v3, 0xc800, v3
	ds_write2_b64 v3, v[32:33], v[34:35] offset1:2
	v_add_u32_e32 v3, 0, v190
	v_add_u32_e32 v3, 0xc800, v3
	ds_write2_b64 v3, v[36:37], v[38:39] offset1:2
	v_mul_u32_u24_e32 v3, 0x190, v216
	v_add3_u32 v221, 0, v3, v186
	v_lshlrev_b32_e32 v3, 8, v216
	v_sub_u32_e32 v217, v221, v3
	v_mad_i64_i32 v[2:3], s[0:1], v41, s4, v[0:1]
	v_mad_i64_i32 v[0:1], s[0:1], v19, s4, v[0:1]
	v_or_b32_e32 v2, v2, v7
	v_or_b32_e32 v0, v0, v7
	v_lshl_add_u64 v[202:203], s[74:75], 0, v[2:3]
	v_lshl_add_u64 v[204:205], s[74:75], 0, v[0:1]
	v_mov_b32_e32 v0, v165
	v_mov_b32_e32 v1, v165
	v_mov_b32_e32 v2, v165
	v_mov_b32_e32 v3, v165
	v_mov_b32_e32 v7, v165
	v_mov_b64_e32 v[62:63], v[14:15]
	v_mov_b64_e32 v[46:47], v[14:15]
	v_mov_b64_e32 v[30:31], v[14:15]
	v_mov_b64_e32 v[60:61], v[12:13]
	v_mov_b64_e32 v[58:59], v[10:11]
	v_mov_b64_e32 v[56:57], v[8:9]
	v_mov_b64_e32 v[54:55], v[6:7]
	v_mov_b64_e32 v[52:53], v[4:5]
	v_mov_b64_e32 v[50:51], v[2:3]
	v_mov_b64_e32 v[48:49], v[0:1]
	v_mov_b64_e32 v[44:45], v[12:13]
	v_mov_b64_e32 v[42:43], v[10:11]
	v_mov_b64_e32 v[40:41], v[8:9]
	v_mov_b64_e32 v[38:39], v[6:7]
	v_mov_b64_e32 v[36:37], v[4:5]
	v_mov_b64_e32 v[34:35], v[2:3]
	v_mov_b64_e32 v[32:33], v[0:1]
	v_mov_b64_e32 v[28:29], v[12:13]
	v_mov_b64_e32 v[26:27], v[10:11]
	v_mov_b64_e32 v[24:25], v[8:9]
	v_mov_b64_e32 v[22:23], v[6:7]
	v_mov_b64_e32 v[20:21], v[4:5]
	v_mov_b64_e32 v[18:19], v[2:3]
	v_mov_b64_e32 v[16:17], v[0:1]
	s_waitcnt lgkmcnt(0)
	s_barrier
	v_readfirstlane_b32 s0, v206
	s_nop 3
	s_lshr_b32 s100, s0, 8
	s_cmp_ge_u32 s0, 0x100
	s_cbranch_scc1 .Lat_prio
	s_setprio 1
.Lat_prio:
.LBB0_904:
	s_and_b32 s16, s9, 1
	s_cmp_gt_i32 s9, s10
	s_cselect_b64 s[0:1], -1, 0
	s_or_b64 s[0:1], s[22:23], s[0:1]
	s_and_b64 vcc, exec, s[0:1]
	s_cbranch_vccnz .LBB0_909
	s_cmp_eq_u32 s100, 0
	s_cbranch_scc1 .Lat_nosl
	s_sleep 2
; #define LAS __attribute__((address_space(3)))
; __device__ __forceinline__ int crow(int r, int hi) { return (r & 3) + 8 * (r >> 2) + 4 * hi; }
; #define MFMA32(a, b, c) __builtin_amdgcn_mfma_f32_32x32x16_bf16((a), (b), (c), 0, 0, 0)
; __device__ __forceinline__ void unit(LAS unsigned char* lds, const Tensors& T, int h, int qrow0, int nact, bool sample, int limbase, int kv0, int kvnew, int nt) {
;     ...
;         if (active && t <= lim) {
;             const LAS unsigned char* kp = lds + OFF_K + buf * KBUF + r32 * KP + hi * 16;
;             f32x16 p0, p1;
; #pragma unroll
;             for (int r = 0; r < 16; ++r) { p0[r] = 0.f; p1[r] = 0.f; }
;             { bf16x8 kf[4][2];
; #pragma unroll
;               for (int i = 0; i < 4; ++i) { kf[i][0] = *(const LAS bf16x8*)(kp + i * 32); kf[i][1] = *(const LAS bf16x8*)(kp + 32 * KP + i * 32); }
;               __builtin_amdgcn_sched_barrier(0);
; #pragma unroll
;               for (int i = 0; i < 12; ++i) {
;                   p0 = MFMA32(kf[i & 3][0], qf[i], p0); p1 = MFMA32(kf[i & 3][1], qf[i], p1);
;                   if (i + 4 < 12) { kf[i & 3][0] = *(const LAS bf16x8*)(kp + (i + 4) * 32); kf[i & 3][1] = *(const LAS bf16x8*)(kp + 32 * KP + (i + 4) * 32); }
;                   __builtin_amdgcn_sched_barrier(0);
;               } }
;             float rm = fmaxf(p0[0], p1[0]);
; #pragma unroll
;             for (int r = 1; r < 16; ++r) rm = fmaxf(rm, fmaxf(p0[r], p1[r]));
;             { const auto rr = __builtin_amdgcn_permlane32_swap(__float_as_uint(rm), __float_as_uint(rm), false, false);
;               rm = fmaxf(__uint_as_float(rr[0]), __uint_as_float(rr[1])); }
;             const bool need = rm > mrun + 8.0f;
;             if (__builtin_amdgcn_ballot_w64(need) != 0ull) {
;                 const float mn = need ? rm : mrun; const float alpha = __builtin_amdgcn_exp2f(mrun - mn); mrun = mn; lrun *= alpha;
;                 if (hi == 0) scr[r32] = alpha;
;                 asm volatile("s_waitcnt lgkmcnt(0)" ::: "memory");
; #pragma unroll
;                 for (int r = 0; r < 16; ++r) { const float f = scr[crow(r, hi)];
; #pragma unroll
;                     for (int d = 0; d < 4; ++d) o[d][r] *= f; }
;                 asm volatile("s_waitcnt lgkmcnt(0)" ::: "memory");
;             }
.Lat_nosl:
	s_mul_i32 s0, s16, 0x6400
	v_add_u32_e32 v222, s0, v221
	ds_read_b128 v[64:67], v222
	ds_read_b128 v[224:227], v222 offset:32
	ds_read_b128 v[68:71], v222 offset:12800
	ds_read_b128 v[228:231], v222 offset:12832
	ds_read_b128 v[232:235], v222 offset:64
	ds_read_b128 v[236:239], v222 offset:96
	ds_read_b128 v[240:243], v222 offset:12864
	ds_read_b128 v[244:247], v222 offset:12896
	global_load_dwordx4 v[160:163], v[198:199], off
	global_load_dwordx4 v[156:159], v[194:195], off
	global_load_dwordx4 v[152:155], v[192:193], off
	global_load_dwordx4 v[148:151], v[204:205], off
	global_load_dwordx4 v[144:147], v[202:203], off
	s_waitcnt lgkmcnt(7)
	v_mfma_f32_32x32x16_bf16 v[80:95], v[64:67], v[140:143], 0
	ds_read_b128 v[248:251], v222 offset:128
	ds_read_b128 v[166:169], v222 offset:12928
	s_waitcnt lgkmcnt(7)
	v_mfma_f32_32x32x16_bf16 v[64:79], v[68:71], v[140:143], 0
	v_mfma_f32_32x32x16_bf16 v[80:95], v[224:227], v[136:139], v[80:95]
	s_waitcnt lgkmcnt(6)
	v_mfma_f32_32x32x16_bf16 v[64:79], v[228:231], v[136:139], v[64:79]
	ds_read_b128 v[224:227], v222 offset:160
	ds_read_b128 v[228:231], v222 offset:12960
	s_waitcnt lgkmcnt(7)
	v_mfma_f32_32x32x16_bf16 v[80:95], v[232:235], v[132:135], v[80:95]
	s_waitcnt lgkmcnt(5)
	v_mfma_f32_32x32x16_bf16 v[64:79], v[240:243], v[132:135], v[64:79]
	ds_read_b128 v[232:235], v222 offset:192
	ds_read_b128 v[240:243], v222 offset:12992
	v_mfma_f32_32x32x16_bf16 v[80:95], v[236:239], v[128:131], v[80:95]
	s_waitcnt lgkmcnt(6)
	v_mfma_f32_32x32x16_bf16 v[64:79], v[244:247], v[128:131], v[64:79]
	ds_read_b128 v[236:239], v222 offset:224
	ds_read_b128 v[244:247], v222 offset:13024
	s_waitcnt lgkmcnt(7)
	v_mfma_f32_32x32x16_bf16 v[80:95], v[248:251], v[124:127], v[80:95]
	s_waitcnt lgkmcnt(6)
	v_mfma_f32_32x32x16_bf16 v[64:79], v[166:169], v[124:127], v[64:79]
	ds_read_b128 v[166:169], v222 offset:256
	ds_read_b128 v[248:251], v222 offset:13056
	s_waitcnt lgkmcnt(7)
	v_mfma_f32_32x32x16_bf16 v[80:95], v[224:227], v[120:123], v[80:95]
	s_waitcnt lgkmcnt(6)
	v_mfma_f32_32x32x16_bf16 v[64:79], v[228:231], v[120:123], v[64:79]
	ds_read_b128 v[224:227], v222 offset:288
	ds_read_b128 v[228:231], v222 offset:13088
	s_waitcnt lgkmcnt(7)
	v_mfma_f32_32x32x16_bf16 v[80:95], v[232:235], v[116:119], v[80:95]
	s_waitcnt lgkmcnt(6)
	v_mfma_f32_32x32x16_bf16 v[64:79], v[240:243], v[116:119], v[64:79]
	ds_read_b128 v[232:235], v222 offset:320
	ds_read_b128 v[240:243], v222 offset:13120
	s_waitcnt lgkmcnt(7)
	v_mfma_f32_32x32x16_bf16 v[80:95], v[236:239], v[112:115], v[80:95]
	s_waitcnt lgkmcnt(6)
	v_mfma_f32_32x32x16_bf16 v[64:79], v[244:247], v[112:115], v[64:79]
	ds_read_b128 v[236:239], v222 offset:352
	ds_read_b128 v[244:247], v222 offset:13152
	s_waitcnt lgkmcnt(7)
	v_mfma_f32_32x32x16_bf16 v[80:95], v[166:169], v[108:111], v[80:95]
	s_waitcnt lgkmcnt(6)
	v_mfma_f32_32x32x16_bf16 v[64:79], v[248:251], v[108:111], v[64:79]
	s_waitcnt lgkmcnt(5)
	v_mfma_f32_32x32x16_bf16 v[80:95], v[224:227], v[104:107], v[80:95]
	s_waitcnt lgkmcnt(4)
	v_mfma_f32_32x32x16_bf16 v[64:79], v[228:231], v[104:107], v[64:79]
	s_waitcnt lgkmcnt(3)
	v_mfma_f32_32x32x16_bf16 v[80:95], v[232:235], v[100:103], v[80:95]
	s_waitcnt lgkmcnt(2)
	v_mfma_f32_32x32x16_bf16 v[64:79], v[240:243], v[100:103], v[64:79]
	s_waitcnt lgkmcnt(1)
	v_mfma_f32_32x32x16_bf16 v[80:95], v[236:239], v[96:99], v[80:95]
	s_waitcnt lgkmcnt(0)
	v_mfma_f32_32x32x16_bf16 v[64:79], v[244:247], v[96:99], v[64:79]
	s_nop 11
	v_max3_f32 v224, v64, v65, v66
	v_max3_f32 v225, v67, v68, v69
	v_max3_f32 v226, v70, v71, v72
	v_max3_f32 v227, v73, v74, v75
	v_max3_f32 v228, v76, v77, v78
	v_max3_f32 v229, v79, v80, v81
	v_max3_f32 v230, v82, v83, v84
	v_max3_f32 v231, v85, v86, v87
	v_max3_f32 v232, v88, v89, v90
	v_max3_f32 v233, v91, v92, v93
	v_max3_f32 v224, v224, v225, v226
	v_max3_f32 v227, v227, v228, v229
	v_max3_f32 v230, v230, v231, v232
	v_max3_f32 v233, v233, v94, v95
	v_max3_f32 v224, v224, v227, v230
	v_max_f32_e32 v166, v224, v233
	v_mov_b32_e32 v167, v166
	s_nop 1
	v_permlane32_swap_b32_e32 v166, v167
	v_max_f32_e32 v222, v166, v167
	v_add_f32_e32 v166, 0x41000000, v223
	v_cmp_gt_f32_e32 vcc, v222, v166
	s_cbranch_vccz .LBB0_910
	s_nop 0
	v_cndmask_b32_e32 v222, v223, v222, vcc
	v_sub_f32_e32 v166, v223, v222
	v_exp_f32_e32 v223, v166
	s_and_saveexec_b64 s[0:1], s[38:39]
	ds_write_b32 v189, v223
	s_or_b64 exec, exec, s[0:1]
	v_mul_f32_e32 v191, v191, v223
	s_waitcnt lgkmcnt(0)
	v_add_u32_e32 v223, s12, v186
	ds_read_b128 v[166:169], v223
	ds_read_b128 v[224:227], v223 offset:32
	ds_read_b128 v[228:231], v223 offset:64
	ds_read_b128 v[232:235], v223 offset:96
	s_waitcnt lgkmcnt(0)
	s_waitcnt lgkmcnt(3)
	v_pk_mul_f32 v[2:3], v[2:3], v[168:169]
	s_waitcnt lgkmcnt(2)
	v_pk_mul_f32 v[4:5], v[4:5], v[224:225]
	s_waitcnt lgkmcnt(1)
	v_pk_mul_f32 v[8:9], v[8:9], v[228:229]
	s_waitcnt lgkmcnt(0)
	v_pk_mul_f32 v[12:13], v[12:13], v[232:233]
	v_pk_mul_f32 v[14:15], v[14:15], v[234:235]
	v_pk_mul_f32 v[10:11], v[10:11], v[230:231]
	v_pk_mul_f32 v[6:7], v[6:7], v[226:227]
	v_pk_mul_f32 v[0:1], v[0:1], v[166:167]
	v_pk_mul_f32 v[60:61], v[60:61], v[232:233]
	v_pk_mul_f32 v[56:57], v[56:57], v[228:229]
	v_pk_mul_f32 v[52:53], v[52:53], v[224:225]
	v_pk_mul_f32 v[62:63], v[62:63], v[234:235]
	v_pk_mul_f32 v[58:59], v[58:59], v[230:231]
	v_pk_mul_f32 v[54:55], v[54:55], v[226:227]
	v_pk_mul_f32 v[50:51], v[50:51], v[168:169]
	v_pk_mul_f32 v[48:49], v[48:49], v[166:167]
	v_pk_mul_f32 v[44:45], v[44:45], v[232:233]
	v_pk_mul_f32 v[40:41], v[40:41], v[228:229]
	v_pk_mul_f32 v[36:37], v[36:37], v[224:225]
	v_pk_mul_f32 v[46:47], v[46:47], v[234:235]
	v_pk_mul_f32 v[42:43], v[42:43], v[230:231]
	v_pk_mul_f32 v[38:39], v[38:39], v[226:227]
	v_pk_mul_f32 v[34:35], v[34:35], v[168:169]
	v_pk_mul_f32 v[32:33], v[32:33], v[166:167]
	v_pk_mul_f32 v[28:29], v[28:29], v[232:233]
	v_pk_mul_f32 v[24:25], v[24:25], v[228:229]
	v_pk_mul_f32 v[20:21], v[20:21], v[224:225]
	v_pk_mul_f32 v[30:31], v[30:31], v[234:235]
	v_pk_mul_f32 v[26:27], v[26:27], v[230:231]
	v_pk_mul_f32 v[22:23], v[22:23], v[226:227]
	v_pk_mul_f32 v[18:19], v[18:19], v[168:169]
	v_pk_mul_f32 v[16:17], v[16:17], v[166:167]
	s_branch .LBB0_911
